# P1 modulation: all norm1_g/shift/scale loads of an iteration issued at the loop top (same as the P7 change)
# speedup vs baseline: 1.0241x; 1.0031x over previous
; DI unsigned pk_bf16(float lo, float hi) { f32x2v v = {lo, hi}; bf16x2v b = __builtin_convertvector(v, bf16x2v); return __builtin_bit_cast(unsigned, b); }
; DI void phase1(const Params& p) {
;     ...
;   for (int R0 = gw; R0 < NT + NC; R0 += 2 * nw) {
;     const int R1 = R0 + nw; const bool has1 = R1 < NT + NC;
;     const float* src0 = (R0 < NT) ? p.x + (size_t)R0 * DM : p.ctx + (size_t)(R0 - NT) * DM;
;     const float* src1 = has1 ? ((R1 < NT) ? p.x + (size_t)R1 * DM : p.ctx + (size_t)(R1 - NT) * DM) : src0;
;     const float* md0 = p.mod + ((R0 < NT) ? (R0 >> 11) : 32) * 6144;
;     const float* md1 = p.mod + ((has1 && R1 < NT) ? (R1 >> 11) : 32) * 6144;
;     float4 v0[4], v1[4]; float s0 = 0.f, s1 = 0.f;
; #pragma unroll
;     for (int i = 0; i < 4; ++i) { v0[i] = *(const float4*)(src0 + lane * 4 + 256 * i); v1[i] = *(const float4*)(src1 + lane * 4 + 256 * i); }
; #pragma unroll
;     for (int i = 0; i < 4; ++i) { s0 += v0[i].x * v0[i].x + v0[i].y * v0[i].y + v0[i].z * v0[i].z + v0[i].w * v0[i].w; s1 += v1[i].x * v1[i].x + v1[i].y * v1[i].y + v1[i].z * v1[i].z + v1[i].w * v1[i].w; }
;     s0 = wave_sum(s0); s1 = wave_sum(s1);
;     const float r0 = rsqrtf(s0 * (1.f / DM) + EPS), r1 = rsqrtf(s1 * (1.f / DM) + EPS);
; #pragma unroll
;     for (int i = 0; i < 4; ++i) {
;       const int d = lane * 4 + 256 * i;
;       const float4 g = *(const float4*)(p.norm1_g + d);
;       {
;         const float4 sh = *(const float4*)(md0 + d), sc = *(const float4*)(md0 + 1024 + d);
;         uint2 o; o.x = pk_bf16(v0[i].x * r0 * g.x * (1.f + sc.x) + sh.x, v0[i].y * r0 * g.y * (1.f + sc.y) + sh.y);
;         o.y = pk_bf16(v0[i].z * r0 * g.z * (1.f + sc.z) + sh.z, v0[i].w * r0 * g.w * (1.f + sc.w) + sh.w);
;         *(uint2*)(p.h + (size_t)R0 * DM + d) = o;
;       }
;       if (has1) {
;         const float4 sh = *(const float4*)(md1 + d), sc = *(const float4*)(md1 + 1024 + d);
;         uint2 o; o.x = pk_bf16(v1[i].x * r1 * g.x * (1.f + sc.x) + sh.x, v1[i].y * r1 * g.y * (1.f + sc.y) + sh.y);
;         o.y = pk_bf16(v1[i].z * r1 * g.z * (1.f + sc.z) + sh.z, v1[i].w * r1 * g.w * (1.f + sc.w) + sh.w);
;         *(uint2*)(p.h + (size_t)R1 * DM + d) = o;
;       }
;     }
.LBB0_109:
	s_or_b64 exec, exec, s[6:7]
	v_lshl_add_u64 v[30:31], v[4:5], 0, v[56:57]
	v_lshl_add_u64 v[32:33], v[2:3], 0, v[56:57]
	global_load_dwordx4 v[14:17], v[30:31], off offset:2048
	global_load_dwordx4 v[6:9], v[30:31], off offset:3072
	global_load_dwordx4 v[10:13], v[32:33], off offset:2048
	global_load_dwordx4 v[2:5], v[32:33], off offset:3072
	global_load_dwordx4 v[26:29], v[32:33], off
	global_load_dwordx4 v[18:21], v[32:33], off offset:1024
	global_load_dwordx4 v[82:85], v[30:31], off
	global_load_dwordx4 v[22:25], v[30:31], off offset:1024
	v_min_i32_e32 v36, 0x10000, v80
	v_ashrrev_i32_e32 v36, 11, v36
	v_mul_i32_i24_e32 v60, 0x1800, v36
	v_ashrrev_i32_e32 v61, 31, v60
	v_lshl_add_u64 v[60:61], v[60:61], 2, s[8:9]
	v_lshl_add_u64 v[62:63], v[60:61], 0, s[24:25]
	v_lshl_add_u64 v[60:61], v[60:61], 0, v[56:57]
	global_load_dwordx4 v[30:33], v[44:45], off
	v_lshl_add_u64 v[64:65], v[62:63], 0, v[56:57]
	global_load_dwordx4 v[86:89], v[60:61], off
	global_load_dwordx4 v[90:93], v[64:65], off
	v_min_i32_e32 v36, 0x10000, v55
	v_ashrrev_i32_e32 v36, 11, v36
	v_mul_i32_i24_e32 v202, 0x1800, v36
	v_ashrrev_i32_e32 v203, 31, v202
	v_lshl_add_u64 v[202:203], v[202:203], 2, s[8:9]
	v_lshl_add_u64 v[204:205], v[202:203], 0, s[24:25]
	v_lshl_add_u64 v[202:203], v[202:203], 0, v[56:57]
	v_lshl_add_u64 v[204:205], v[204:205], 0, v[56:57]
	global_load_dwordx4 v[170:173], v[204:205], off
	global_load_dwordx4 v[186:189], v[202:203], off
	global_load_dwordx4 v[134:137], v[44:45], off offset:1024
	global_load_dwordx4 v[146:149], v[64:65], off offset:1024
	global_load_dwordx4 v[158:161], v[60:61], off offset:1024
	global_load_dwordx4 v[174:177], v[204:205], off offset:1024
	global_load_dwordx4 v[190:193], v[202:203], off offset:1024
	global_load_dwordx4 v[138:141], v[44:45], off offset:2048
	global_load_dwordx4 v[150:153], v[64:65], off offset:2048
	global_load_dwordx4 v[162:165], v[60:61], off offset:2048
	global_load_dwordx4 v[178:181], v[204:205], off offset:2048
	global_load_dwordx4 v[194:197], v[202:203], off offset:2048
	global_load_dwordx4 v[142:145], v[44:45], off offset:3072
	global_load_dwordx4 v[154:157], v[64:65], off offset:3072
	global_load_dwordx4 v[166:169], v[60:61], off offset:3072
	global_load_dwordx4 v[182:185], v[204:205], off offset:3072
	global_load_dwordx4 v[198:201], v[202:203], off offset:3072
	s_waitcnt vmcnt(25)
	v_mov_b32_e32 v94, v11
	s_waitcnt vmcnt(24)
	v_mov_b32_e32 v95, v3
	s_waitcnt vmcnt(23)
	v_mov_b32_e32 v102, v27
	v_mov_b32_e32 v68, v15
	v_mov_b32_e32 v69, v7
	s_waitcnt vmcnt(22)
	v_mov_b32_e32 v103, v19
	s_waitcnt vmcnt(21)
	v_mov_b32_e32 v114, v83
	s_waitcnt vmcnt(20)
	v_mov_b32_e32 v115, v23
	v_mov_b32_e32 v64, v14
	v_mov_b32_e32 v65, v6
	v_mov_b32_e32 v74, v10
	v_mov_b32_e32 v75, v2
	v_mov_b32_e32 v100, v26
	v_mov_b32_e32 v101, v18
	v_mov_b32_e32 v112, v82
	v_mov_b32_e32 v113, v22
	v_pk_mul_f32 v[68:69], v[68:69], v[68:69]
	v_pk_mul_f32 v[94:95], v[94:95], v[94:95]
	v_pk_mul_f32 v[102:103], v[102:103], v[102:103]
	v_pk_mul_f32 v[114:115], v[114:115], v[114:115]
	v_mov_b32_e32 v70, v16
	v_mov_b32_e32 v71, v8
	v_mov_b32_e32 v104, v28
	v_mov_b32_e32 v105, v20
	v_mov_b32_e32 v108, v84
	v_mov_b32_e32 v109, v24
	v_pk_fma_f32 v[64:65], v[64:65], v[64:65], v[68:69]
	v_pk_fma_f32 v[68:69], v[74:75], v[74:75], v[94:95]
	v_pk_fma_f32 v[74:75], v[100:101], v[100:101], v[102:103]
	v_pk_fma_f32 v[94:95], v[112:113], v[112:113], v[114:115]
	v_mov_b32_e32 v72, v17
	v_mov_b32_e32 v73, v9
	v_mov_b32_e32 v96, v12
	v_mov_b32_e32 v97, v4
	v_mov_b32_e32 v106, v29
	v_mov_b32_e32 v107, v21
	v_mov_b32_e32 v110, v85
	v_mov_b32_e32 v111, v25
	v_pk_fma_f32 v[64:65], v[70:71], v[70:71], v[64:65]
	v_pk_fma_f32 v[70:71], v[104:105], v[104:105], v[74:75]
	v_pk_fma_f32 v[74:75], v[108:109], v[108:109], v[94:95]
	v_mov_b32_e32 v98, v13
	v_mov_b32_e32 v99, v5
	v_pk_fma_f32 v[68:69], v[96:97], v[96:97], v[68:69]
	v_pk_fma_f32 v[64:65], v[72:73], v[72:73], v[64:65]
	v_pk_fma_f32 v[70:71], v[106:107], v[106:107], v[70:71]
	v_pk_fma_f32 v[72:73], v[110:111], v[110:111], v[74:75]
	v_pk_fma_f32 v[68:69], v[98:99], v[98:99], v[68:69]
	v_mov_b32_e32 v74, v70
	v_mov_b32_e32 v75, v72
	v_mov_b32_e32 v72, v71
	v_mov_b32_e32 v70, v68
	v_mov_b32_e32 v71, v64
	v_mov_b32_e32 v64, v69
	v_pk_add_f32 v[68:69], v[74:75], v[72:73]
	v_lshl_add_u64 v[72:73], v[50:51], 0, v[46:47]
	v_pk_add_f32 v[68:69], v[68:69], v[70:71]
	s_nop 0
	v_pk_add_f32 v[64:65], v[68:69], v[64:65]
	ds_bpermute_b32 v68, v1, v64
	ds_bpermute_b32 v69, v1, v65
	s_waitcnt lgkmcnt(0)
	v_pk_add_f32 v[64:65], v[64:65], v[68:69]
	ds_bpermute_b32 v68, v39, v64
	ds_bpermute_b32 v69, v39, v65
	s_waitcnt lgkmcnt(0)
	v_pk_add_f32 v[64:65], v[64:65], v[68:69]
	ds_bpermute_b32 v68, v41, v64
	ds_bpermute_b32 v69, v41, v65
	s_waitcnt lgkmcnt(0)
	v_pk_add_f32 v[64:65], v[64:65], v[68:69]
	ds_bpermute_b32 v68, v43, v64
	ds_bpermute_b32 v69, v43, v65
	s_waitcnt lgkmcnt(0)
	v_pk_add_f32 v[64:65], v[64:65], v[68:69]
	ds_bpermute_b32 v68, v59, v64
	ds_bpermute_b32 v69, v59, v65
	s_waitcnt lgkmcnt(0)
	v_pk_add_f32 v[70:71], v[64:65], v[68:69]
	ds_bpermute_b32 v74, v67, v70
	ds_bpermute_b32 v75, v67, v71
	v_mul_i32_i24_e32 v64, 0x1800, v36
	v_ashrrev_i32_e32 v65, 31, v64
	v_lshl_add_u64 v[64:65], v[64:65], 2, s[8:9]
	v_lshl_add_u64 v[68:69], v[64:65], 0, s[24:25]
	s_waitcnt lgkmcnt(0)
	v_pk_add_f32 v[70:71], v[70:71], v[74:75]
	s_nop 0
	v_pk_fma_f32 v[70:71], v[70:71], s[26:27], v[58:59] op_sel_hi:[1,0,0]
	s_nop 0
	v_mul_f32_e32 v55, 0x4b800000, v71
	v_cmp_gt_f32_e64 s[6:7], s34, v71
	v_mul_f32_e32 v36, 0x4b800000, v70
	v_cmp_gt_f32_e64 s[4:5], s34, v70
	v_cndmask_b32_e64 v55, v71, v55, s[6:7]
	v_rsq_f32_e32 v55, v55
	v_cndmask_b32_e64 v36, v70, v36, s[4:5]
	v_rsq_f32_e32 v36, v36
	s_waitcnt vmcnt(17)
	v_pk_add_f32 v[70:71], v[90:91], 1.0 op_sel_hi:[1,0]
	v_mul_f32_e32 v74, 0x45800000, v55
	v_cndmask_b32_e64 v74, v55, v74, s[6:7]
	v_pk_mul_f32 v[82:83], v[82:83], v[74:75] op_sel_hi:[1,0]
	v_pk_mul_f32 v[84:85], v[84:85], v[74:75] op_sel_hi:[1,0]
	v_pk_add_f32 v[90:91], v[92:93], 1.0 op_sel_hi:[1,0]
	v_pk_mul_f32 v[82:83], v[30:31], v[82:83]
	v_pk_mul_f32 v[84:85], v[32:33], v[84:85]
	v_pk_fma_f32 v[70:71], v[82:83], v[70:71], v[86:87]
	v_pk_fma_f32 v[82:83], v[84:85], v[90:91], v[88:89]
	v_mul_f32_e32 v66, 0x45800000, v36
	v_cvt_pk_bf16_f32 v70, v70, v71
	v_cvt_pk_bf16_f32 v71, v82, v83
	v_cndmask_b32_e64 v66, v36, v66, s[4:5]
	global_store_dwordx2 v[72:73], v[70:71], off
	v_lshl_add_u64 v[70:71], v[48:49], 0, v[46:47]
	s_and_saveexec_b64 s[4:5], vcc
	s_cbranch_execz .LBB0_111
; DI unsigned pk_bf16(float lo, float hi) { f32x2v v = {lo, hi}; bf16x2v b = __builtin_convertvector(v, bf16x2v); return __builtin_bit_cast(unsigned, b); }
; DI void phase1(const Params& p) {
;     ...
;     for (int i = 0; i < 4; ++i) {
;       const int d = lane * 4 + 256 * i;
;       const float4 g = *(const float4*)(p.norm1_g + d);
;       {
;         const float4 sh = *(const float4*)(md0 + d), sc = *(const float4*)(md0 + 1024 + d);
;         uint2 o; o.x = pk_bf16(v0[i].x * r0 * g.x * (1.f + sc.x) + sh.x, v0[i].y * r0 * g.y * (1.f + sc.y) + sh.y);
;         o.y = pk_bf16(v0[i].z * r0 * g.z * (1.f + sc.z) + sh.z, v0[i].w * r0 * g.w * (1.f + sc.w) + sh.w);
;         *(uint2*)(p.h + (size_t)R0 * DM + d) = o;
;       }
;       if (has1) {
;         const float4 sh = *(const float4*)(md1 + d), sc = *(const float4*)(md1 + 1024 + d);
;         uint2 o; o.x = pk_bf16(v1[i].x * r1 * g.x * (1.f + sc.x) + sh.x, v1[i].y * r1 * g.y * (1.f + sc.y) + sh.y);
;         o.y = pk_bf16(v1[i].z * r1 * g.z * (1.f + sc.z) + sh.z, v1[i].w * r1 * g.w * (1.f + sc.w) + sh.w);
;         *(uint2*)(p.h + (size_t)R1 * DM + d) = o;
;       }
;     }
	s_waitcnt vmcnt(16)
	v_pk_mul_f32 v[26:27], v[26:27], v[66:67] op_sel_hi:[1,0]
	v_pk_mul_f32 v[28:29], v[28:29], v[66:67] op_sel_hi:[1,0]
	v_pk_mul_f32 v[26:27], v[30:31], v[26:27]
	v_pk_mul_f32 v[28:29], v[32:33], v[28:29]
	v_pk_add_f32 v[30:31], v[170:171], 1.0 op_sel_hi:[1,0]
	v_pk_add_f32 v[32:33], v[172:173], 1.0 op_sel_hi:[1,0]
	v_pk_fma_f32 v[26:27], v[26:27], v[30:31], v[186:187]
	v_pk_fma_f32 v[28:29], v[28:29], v[32:33], v[188:189]
	v_cvt_pk_bf16_f32 v26, v26, v27
	v_cvt_pk_bf16_f32 v27, v28, v29
	global_store_dwordx2 v[70:71], v[26:27], off
.LBB0_111:
	s_or_b64 exec, exec, s[4:5]
	s_waitcnt vmcnt(13)
	v_lshlrev_b32_e32 v36, 2, v38
	v_mov_b32_e32 v75, v74
	v_pk_mul_f32 v[22:23], v[22:23], v[74:75]
	v_pk_mul_f32 v[24:25], v[24:25], v[74:75]
	v_pk_mul_f32 v[22:23], v[22:23], v[134:135]
	v_pk_mul_f32 v[24:25], v[24:25], v[136:137]
	v_pk_add_f32 v[146:147], v[146:147], 1.0 op_sel_hi:[1,0]
	v_pk_add_f32 v[148:149], v[148:149], 1.0 op_sel_hi:[1,0]
	v_pk_fma_f32 v[22:23], v[22:23], v[146:147], v[158:159]
	v_pk_fma_f32 v[24:25], v[24:25], v[148:149], v[160:161]
	v_cvt_pk_bf16_f32 v22, v22, v23
	v_cvt_pk_bf16_f32 v23, v24, v25
	global_store_dwordx2 v[72:73], v[22:23], off offset:512
	s_and_saveexec_b64 s[4:5], vcc
	s_cbranch_execz .LBB0_113
	s_waitcnt vmcnt(13)
	v_mov_b32_e32 v55, v37
	v_pk_mul_f32 v[18:19], v[18:19], v[66:67] op_sel_hi:[1,0]
	v_pk_mul_f32 v[20:21], v[20:21], v[66:67] op_sel_hi:[1,0]
	v_pk_mul_f32 v[18:19], v[18:19], v[134:135]
	v_pk_mul_f32 v[20:21], v[20:21], v[136:137]
	v_pk_add_f32 v[174:175], v[174:175], 1.0 op_sel_hi:[1,0]
	v_pk_add_f32 v[176:177], v[176:177], 1.0 op_sel_hi:[1,0]
	v_pk_fma_f32 v[18:19], v[18:19], v[174:175], v[190:191]
	v_pk_fma_f32 v[20:21], v[20:21], v[176:177], v[192:193]
	v_cvt_pk_bf16_f32 v18, v18, v19
	v_cvt_pk_bf16_f32 v19, v20, v21
	global_store_dwordx2 v[70:71], v[18:19], off offset:512
.LBB0_113:
	s_or_b64 exec, exec, s[4:5]
	s_waitcnt vmcnt(9)
	v_lshlrev_b32_e32 v36, 2, v40
	v_pk_mul_f32 v[14:15], v[14:15], v[74:75]
	v_pk_mul_f32 v[16:17], v[16:17], v[74:75]
	v_pk_mul_f32 v[14:15], v[14:15], v[138:139]
	v_pk_mul_f32 v[16:17], v[16:17], v[140:141]
	v_pk_add_f32 v[150:151], v[150:151], 1.0 op_sel_hi:[1,0]
	v_pk_add_f32 v[152:153], v[152:153], 1.0 op_sel_hi:[1,0]
	v_pk_fma_f32 v[14:15], v[14:15], v[150:151], v[162:163]
	v_pk_fma_f32 v[16:17], v[16:17], v[152:153], v[164:165]
	v_cvt_pk_bf16_f32 v14, v14, v15
	v_cvt_pk_bf16_f32 v15, v16, v17
	global_store_dwordx2 v[72:73], v[14:15], off offset:1024
	s_and_saveexec_b64 s[4:5], vcc
	s_cbranch_execz .LBB0_115
	s_waitcnt vmcnt(10)
	v_mov_b32_e32 v55, v37
	v_pk_mul_f32 v[10:11], v[10:11], v[66:67] op_sel_hi:[1,0]
	v_pk_mul_f32 v[12:13], v[12:13], v[66:67] op_sel_hi:[1,0]
	v_pk_mul_f32 v[10:11], v[10:11], v[138:139]
	v_pk_mul_f32 v[12:13], v[12:13], v[140:141]
	v_pk_add_f32 v[178:179], v[178:179], 1.0 op_sel_hi:[1,0]
	v_pk_add_f32 v[180:181], v[180:181], 1.0 op_sel_hi:[1,0]
	v_pk_fma_f32 v[10:11], v[10:11], v[178:179], v[194:195]
	v_pk_fma_f32 v[12:13], v[12:13], v[180:181], v[196:197]
	v_cvt_pk_bf16_f32 v10, v10, v11
	v_cvt_pk_bf16_f32 v11, v12, v13
	global_store_dwordx2 v[70:71], v[10:11], off offset:1024
.LBB0_115:
	s_or_b64 exec, exec, s[4:5]
	s_waitcnt vmcnt(5)
	v_lshlrev_b32_e32 v36, 2, v42
	v_pk_mul_f32 v[6:7], v[6:7], v[74:75]
	v_pk_mul_f32 v[8:9], v[8:9], v[74:75]
	v_pk_mul_f32 v[6:7], v[6:7], v[142:143]
	v_pk_mul_f32 v[8:9], v[8:9], v[144:145]
	v_pk_add_f32 v[154:155], v[154:155], 1.0 op_sel_hi:[1,0]
	v_pk_add_f32 v[156:157], v[156:157], 1.0 op_sel_hi:[1,0]
	v_pk_fma_f32 v[6:7], v[6:7], v[154:155], v[166:167]
	v_pk_fma_f32 v[8:9], v[8:9], v[156:157], v[168:169]
	v_cvt_pk_bf16_f32 v6, v6, v7
	v_cvt_pk_bf16_f32 v7, v8, v9
	global_store_dwordx2 v[72:73], v[6:7], off offset:1536
	s_and_saveexec_b64 s[4:5], vcc
	s_cbranch_execz .LBB0_102
	s_waitcnt vmcnt(7)
	v_mov_b32_e32 v55, v37
	v_pk_mul_f32 v[2:3], v[2:3], v[66:67] op_sel_hi:[1,0]
	v_pk_mul_f32 v[4:5], v[4:5], v[66:67] op_sel_hi:[1,0]
	v_pk_mul_f32 v[2:3], v[2:3], v[142:143]
	v_pk_mul_f32 v[4:5], v[4:5], v[144:145]
	v_pk_add_f32 v[182:183], v[182:183], 1.0 op_sel_hi:[1,0]
	v_pk_add_f32 v[184:185], v[184:185], 1.0 op_sel_hi:[1,0]
	v_pk_fma_f32 v[2:3], v[2:3], v[182:183], v[198:199]
	v_pk_fma_f32 v[4:5], v[4:5], v[184:185], v[200:201]
	v_cvt_pk_bf16_f32 v2, v2, v3
	v_cvt_pk_bf16_f32 v3, v4, v5
	global_store_dwordx2 v[70:71], v[2:3], off offset:1536
	s_branch .LBB0_102
